# static s_setprio 1 for the two compute waves (0-1) of the attention sample units, which share their SIMDs with staging waves
# speedup vs baseline: 1.0046x; 1.0046x over previous
; #define LAS __attribute__((address_space(3)))
; __device__ __forceinline__ void attn_unit_sample(const Args& a, LAS unsigned char* lds, int b, int h) {
;     int tid_ = threadIdx.x; asm volatile("" : "+v"(tid_));
;     const int tid = tid_, lane = tid & 63, w = __builtin_amdgcn_readfirstlane(tid >> 6), l31 = lane & 31, hi = lane >> 5;
;     const float* cbase = (const float*)(a.ws + WS_CS) + (size_t)(b * 16 + h) * 2112;
;     if (w >= 2 && w < 6) {
;     ...
;     } else {
;         const bool active = w < 2;
;         const int qpos = 2048 + 32 * (w & 1) + l31;
;         const size_t qrow = (size_t)(MP + b * 64 + 32 * (w & 1) + l31);
;         const bf16_t* qkv = (const bf16_t*)(a.ws + WS_PROJ);
;         bf16x8 qf[4];
; #pragma unroll
;         for (int ks = 0; ks < 4; ++ks) qf[ks] = *(const bf16x8*)(qkv + qrow * NPJ + h * 64 + 16 * ks + 8 * hi);
;         const float cq2 = cbase[qpos] * LOG2E;
;         float mrun = -INFINITY, lrun = 0.f;
;         f32x16 ot[2]; ot[0] = f32x16{}; ot[1] = f32x16{};
;         __syncthreads();
; #pragma unroll 1
;         for (int tt = 0; tt < 33; ++tt) {
;             if (active) attn_tile<false>(lds + (tt & 1) * AT_BUF, qf, nullptr, cq2, qpos, 64 * (32 - tt), tt == 0, mrun, lrun, ot, l31, hi);
;             __syncthreads();
;         }
.LBB0_1646:
	s_setprio 0
	v_readfirstlane_b32 s98, v0
	s_nop 3
	s_lshr_b32 s98, s98, 6
	s_cmp_ge_u32 s98, 2
	s_cbranch_scc1 .Lp10_sprio_done
	s_setprio 1
